# FoX tile body: all eight cumulative-gate LDS reads issued inside the QK section (second four into K quads already consumed), FMAs wait only on the MFMA results
# speedup vs baseline: 1.0041x; 1.0041x over previous
; __device__ __forceinline__ f32x16 mfma32(bf16x8 a, bf16x8 b, f32x16 c) { return __builtin_amdgcn_mfma_f32_32x32x16_bf16(a, b, c, 0, 0, 0); }
; template <int MODE> ...
;     ...
;         const lptr Kt = L + A_KT + buf * 9216, Vt = L + A_VT + vcur * 12288;
;         f32x16 s0, s1;
; #pragma unroll
;         for (int s4 = 0; s4 < 4; ++s4) {
;             const bf16x8 a0 = lds_ld<bf16x8>(Kt + n * KP + s4 * 32 + hl * 16);
;             const bf16x8 a1 = lds_ld<bf16x8>(Kt + (32 + n) * KP + s4 * 32 + hl * 16);
;             if (s4 == 0) { s0 = mfma32(a0, qf[0], negm); s1 = mfma32(a1, qf[0], negm); }
;             else { s0 = mfma32(a0, qf[s4], s0); s1 = mfma32(a1, qf[s4], s1); }
;         }
;         const int kbase = 64 * kt + 4 * hl;
;         const bool far = (MODE == MODE_WIN || MODE == MODE_SEL) ? (wtmin - (64 * kt + 63) >= 128) : false;
;         const bool fmask = (MODE == MODE_FOX) ? (64 * kt + 63 > wtmin) : false;
;         const bool clean = (MODE == MODE_WIN) ? (far && (wtmax - 64 * kt < W)) : false;
;         const float mref = (MODE == MODE_CMP2) ? mfix : ((m == -INFINITY) ? 0.f : m);
;         if (MODE == MODE_FOX) {
; #pragma unroll
;             for (int kb = 0; kb < 2; ++kb)
; #pragma unroll
;                 for (int a = 0; a < 4; ++a) {
;                     const f32x4 c4 = lds_ld<f32x4>(L + A_CB + buf * 256 + (32 * kb + 8 * a + 4 * hl) * 4);
; #pragma unroll
;                     for (int e = 0; e < 4; ++e) { const int r = 4 * a + e; if (kb) s1[r] = s1[r] * SC2 + c4[e]; else s0[r] = s0[r] * SC2 + c4[e]; }
;                 }
;             if (__builtin_amdgcn_readfirstlane((int)fmask)) {
; #pragma unroll
;                 for (int r = 0; r < 16; ++r) {
;                     const int key = kbase + 8 * (r >> 2) + (r & 3);
;                     if (key > t) s0[r] = -INFINITY;
;                     if (key + 32 > t) s1[r] = -INFINITY;
;                 }
;             }
.LBB0_178:
	v_add_u32_e32 v14, v134, v135
	v_add_u32_e32 v0, v136, v135
	v_add_u32_e32 v156, v138, v139
	ds_read_b128 v[170:173], v14 offset:0
	ds_read_b128 v[174:177], v0 offset:0
	ds_read_b128 v[178:181], v14 offset:32
	ds_read_b128 v[182:185], v0 offset:32
	ds_read_b128 v[186:189], v14 offset:64
	ds_read_b128 v[194:197], v0 offset:64
	ds_read_b128 v[198:201], v14 offset:96
	ds_read_b128 v[202:205], v0 offset:96
	ds_read_b128 v[144:147], v135 offset:43008
	ds_read_b128 v[148:151], v135 offset:43040
	ds_read_b128 v[152:155], v135 offset:43072
	ds_read_b128 v[12:15], v135 offset:43104
	s_or_b32 s1, s0, 63
	v_cmp_gt_i32_e32 vcc, s1, v125
	s_waitcnt lgkmcnt(11)
	v_mfma_f32_32x32x16_bf16 v[80:95], v[170:173], v[104:107], v[48:63]
	ds_read_b64_tr_b16 v[206:207], v156 offset:18432
	ds_read_b64_tr_b16 v[208:209], v156 offset:19968
	s_waitcnt lgkmcnt(12)
	v_mfma_f32_32x32x16_bf16 v[64:79], v[174:177], v[104:107], v[48:63]
	ds_read_b64_tr_b16 v[210:211], v156 offset:21504
	ds_read_b64_tr_b16 v[212:213], v156 offset:23040
	s_waitcnt lgkmcnt(13)
	v_mfma_f32_32x32x16_bf16 v[80:95], v[178:181], v[96:99], v[80:95]
	ds_read_b64_tr_b16 v[226:227], v156 offset:24576
	ds_read_b64_tr_b16 v[228:229], v156 offset:26112
	s_waitcnt lgkmcnt(14)
	v_mfma_f32_32x32x16_bf16 v[64:79], v[182:185], v[96:99], v[64:79]
	ds_read_b64_tr_b16 v[230:231], v156 offset:27648
	ds_read_b64_tr_b16 v[232:233], v156 offset:29184
	ds_read_b128 v[170:173], v135 offset:43136
	ds_read_b128 v[174:177], v135 offset:43168
	ds_read_b128 v[178:181], v135 offset:43200
	ds_read_b128 v[182:185], v135 offset:43232
	s_waitcnt lgkmcnt(15)
	v_mfma_f32_32x32x16_bf16 v[80:95], v[186:189], v[100:103], v[80:95]
	ds_read_b64_tr_b16 v[234:235], v156 offset:18496
	ds_read_b64_tr_b16 v[236:237], v156 offset:20032
	s_waitcnt lgkmcnt(15)
	v_mfma_f32_32x32x16_bf16 v[64:79], v[194:197], v[100:103], v[64:79]
	ds_read_b64_tr_b16 v[238:239], v156 offset:21568
	ds_read_b64_tr_b16 v[240:241], v156 offset:23104
	v_cndmask_b32_e64 v0, 0, 1, vcc
	s_nop 0
	v_readfirstlane_b32 s1, v0
	s_bitcmp0_b32 s1, 0
	s_waitcnt lgkmcnt(15)
	v_mfma_f32_32x32x16_bf16 v[80:95], v[198:201], v[108:111], v[80:95]
	ds_read_b64_tr_b16 v[242:243], v156 offset:24640
	ds_read_b64_tr_b16 v[244:245], v156 offset:26176
	s_waitcnt lgkmcnt(15)
	v_mfma_f32_32x32x16_bf16 v[64:79], v[202:205], v[108:111], v[64:79]
	ds_read_b64_tr_b16 v[246:247], v156 offset:27712
	ds_read_b64_tr_b16 v[248:249], v156 offset:29248
	s_waitcnt lgkmcnt(15)
	s_nop 5
	v_fma_f32 v82, v82, s54, v146
	v_fma_f32 v83, v83, s54, v147
	v_fma_f32 v86, v86, s54, v150
	v_fma_f32 v87, v87, s54, v151
	v_fma_f32 v88, v88, s54, v152
	v_fma_f32 v89, v89, s54, v153
	v_fma_f32 v10, v94, s54, v14
	v_fma_f32 v11, v95, s54, v15
	v_fma_f32 v12, v92, s54, v12
	v_fma_f32 v13, v93, s54, v13
	v_fma_f32 v14, v90, s54, v154
	v_fma_f32 v15, v91, s54, v155
	v_fma_f32 v84, v84, s54, v148
	v_fma_f32 v85, v85, s54, v149
	v_fma_f32 v80, v80, s54, v144
	v_fma_f32 v81, v81, s54, v145
	s_waitcnt lgkmcnt(8)
	v_fma_f32 v66, v66, s54, v172
	v_fma_f32 v67, v67, s54, v173
	v_fma_f32 v70, v70, s54, v176
	v_fma_f32 v71, v71, s54, v177
	v_fma_f32 v74, v74, s54, v180
	v_fma_f32 v75, v75, s54, v181
	v_fma_f32 v78, v78, s54, v184
	v_fma_f32 v79, v79, s54, v185
	v_fma_f32 v76, v76, s54, v182
	v_fma_f32 v77, v77, s54, v183
	v_fma_f32 v72, v72, s54, v178
	v_fma_f32 v73, v73, s54, v179
	v_fma_f32 v68, v68, s54, v174
	v_fma_f32 v69, v69, s54, v175
	v_fma_f32 v64, v64, s54, v170
	v_fma_f32 v65, v65, s54, v171
	s_cbranch_scc1 .LBB0_180
	v_or_b32_e32 v0, s0, v137
	v_or_b32_e32 v90, 32, v0
	v_cmp_le_i32_e32 vcc, v90, v126
	v_or_b32_e32 v90, 33, v0
	s_nop 0
	v_cndmask_b32_e32 v64, v220, v64, vcc
	v_cmp_lt_i32_e32 vcc, v0, v126
	s_nop 1
	v_cndmask_b32_e32 v81, v220, v81, vcc
	v_cmp_le_i32_e32 vcc, v0, v126
	s_nop 1
	v_cndmask_b32_e32 v80, v220, v80, vcc
	v_cmp_le_i32_e32 vcc, v90, v126
	v_or_b32_e32 v90, 2, v0
	s_nop 0
	v_cndmask_b32_e32 v65, v220, v65, vcc
	v_cmp_le_i32_e32 vcc, v90, v126
	v_or_b32_e32 v90, 34, v0
	s_nop 0
	v_cndmask_b32_e32 v82, v220, v82, vcc
	v_cmp_le_i32_e32 vcc, v90, v126
	v_or_b32_e32 v90, 3, v0
	s_nop 0
	v_cndmask_b32_e32 v66, v220, v66, vcc
	v_cmp_le_i32_e32 vcc, v90, v126
	v_or_b32_e32 v90, 35, v0
	s_nop 0
	v_cndmask_b32_e32 v83, v220, v83, vcc
	v_cmp_le_i32_e32 vcc, v90, v126
	v_or_b32_e32 v90, 8, v0
	s_nop 0
	v_cndmask_b32_e32 v67, v220, v67, vcc
	v_cmp_le_i32_e32 vcc, v90, v126
	v_or_b32_e32 v90, 40, v0
	s_nop 0
	v_cndmask_b32_e32 v84, v220, v84, vcc
	v_cmp_le_i32_e32 vcc, v90, v126
	v_or_b32_e32 v90, 9, v0
	s_nop 0
	v_cndmask_b32_e32 v68, v220, v68, vcc
	v_cmp_le_i32_e32 vcc, v90, v126
	v_or_b32_e32 v90, 41, v0
	s_nop 0
	v_cndmask_b32_e32 v85, v220, v85, vcc
	v_cmp_le_i32_e32 vcc, v90, v126
	v_or_b32_e32 v90, 10, v0
	s_nop 0
	v_cndmask_b32_e32 v69, v220, v69, vcc
	v_cmp_le_i32_e32 vcc, v90, v126
	v_or_b32_e32 v90, 42, v0
	s_nop 0
	v_cndmask_b32_e32 v86, v220, v86, vcc
	v_cmp_le_i32_e32 vcc, v90, v126
	v_or_b32_e32 v90, 11, v0
	s_nop 0
	v_cndmask_b32_e32 v70, v220, v70, vcc
	v_cmp_le_i32_e32 vcc, v90, v126
	v_or_b32_e32 v90, 43, v0
	s_nop 0
	v_cndmask_b32_e32 v87, v220, v87, vcc
	v_cmp_le_i32_e32 vcc, v90, v126
	v_or_b32_e32 v90, 16, v0
	s_nop 0
	v_cndmask_b32_e32 v71, v220, v71, vcc
	v_cmp_le_i32_e32 vcc, v90, v126
	v_or_b32_e32 v90, 48, v0
	s_nop 0
	v_cndmask_b32_e32 v88, v220, v88, vcc
	v_cmp_le_i32_e32 vcc, v90, v126
	v_or_b32_e32 v90, 17, v0
	s_nop 0
	v_cndmask_b32_e32 v72, v220, v72, vcc
	v_cmp_le_i32_e32 vcc, v90, v126
	v_or_b32_e32 v90, 49, v0
	s_nop 0
	v_cndmask_b32_e32 v89, v220, v89, vcc
	v_cmp_le_i32_e32 vcc, v90, v126
	v_or_b32_e32 v90, 18, v0
	s_nop 0
	v_cndmask_b32_e32 v73, v220, v73, vcc
	v_cmp_le_i32_e32 vcc, v90, v126
	v_or_b32_e32 v90, 50, v0
	s_nop 0
	v_cndmask_b32_e32 v14, v220, v14, vcc
	v_cmp_le_i32_e32 vcc, v90, v126
	v_or_b32_e32 v90, 19, v0
	s_nop 0
	v_cndmask_b32_e32 v74, v220, v74, vcc
	v_cmp_le_i32_e32 vcc, v90, v126
	v_or_b32_e32 v90, 51, v0
	s_nop 0
	v_cndmask_b32_e32 v15, v220, v15, vcc
	v_cmp_le_i32_e32 vcc, v90, v126
	v_or_b32_e32 v90, 24, v0
	s_nop 0
	v_cndmask_b32_e32 v75, v220, v75, vcc
	v_cmp_le_i32_e32 vcc, v90, v126
	v_or_b32_e32 v90, 56, v0
	s_nop 0
	v_cndmask_b32_e32 v12, v220, v12, vcc
	v_cmp_le_i32_e32 vcc, v90, v126
	v_or_b32_e32 v90, 25, v0
	s_nop 0
	v_cndmask_b32_e32 v76, v220, v76, vcc
	v_cmp_le_i32_e32 vcc, v90, v126
	v_or_b32_e32 v90, 57, v0
	s_nop 0
	v_cndmask_b32_e32 v13, v220, v13, vcc
	v_cmp_le_i32_e32 vcc, v90, v126
	v_or_b32_e32 v90, 26, v0
	s_nop 0
	v_cndmask_b32_e32 v77, v220, v77, vcc
	v_cmp_le_i32_e32 vcc, v90, v126
	v_or_b32_e32 v90, 58, v0
	s_nop 0
	v_cndmask_b32_e32 v10, v220, v10, vcc
	v_cmp_le_i32_e32 vcc, v90, v126
	v_or_b32_e32 v90, 27, v0
	v_or_b32_e32 v0, 59, v0
	v_cndmask_b32_e32 v78, v220, v78, vcc
	v_cmp_le_i32_e32 vcc, v90, v126
	s_nop 1
	v_cndmask_b32_e32 v11, v220, v11, vcc
	v_cmp_le_i32_e32 vcc, v0, v126
	s_nop 1
	v_cndmask_b32_e32 v79, v220, v79, vcc

; __device__ __forceinline__ f32x16 mfma32(bf16x8 a, bf16x8 b, f32x16 c) { return __builtin_amdgcn_mfma_f32_32x32x16_bf16(a, b, c, 0, 0, 0); }
; template <int MODE> ...
;     ...
;         const lptr Kt = L + A_KT + buf * 9216, Vt = L + A_VT + vcur * 12288;
;         f32x16 s0, s1;
; #pragma unroll
;         for (int s4 = 0; s4 < 4; ++s4) {
;             const bf16x8 a0 = lds_ld<bf16x8>(Kt + n * KP + s4 * 32 + hl * 16);
;             const bf16x8 a1 = lds_ld<bf16x8>(Kt + (32 + n) * KP + s4 * 32 + hl * 16);
;             if (s4 == 0) { s0 = mfma32(a0, qf[0], negm); s1 = mfma32(a1, qf[0], negm); }
;             else { s0 = mfma32(a0, qf[s4], s0); s1 = mfma32(a1, qf[s4], s1); }
;         }
;         const int kbase = 64 * kt + 4 * hl;
;         const bool far = (MODE == MODE_WIN || MODE == MODE_SEL) ? (wtmin - (64 * kt + 63) >= 128) : false;
;         const bool fmask = (MODE == MODE_FOX) ? (64 * kt + 63 > wtmin) : false;
;         const bool clean = (MODE == MODE_WIN) ? (far && (wtmax - 64 * kt < W)) : false;
;         const float mref = (MODE == MODE_CMP2) ? mfix : ((m == -INFINITY) ? 0.f : m);
;         if (MODE == MODE_FOX) {
; #pragma unroll
;             for (int kb = 0; kb < 2; ++kb)
; #pragma unroll
;                 for (int a = 0; a < 4; ++a) {
;                     const f32x4 c4 = lds_ld<f32x4>(L + A_CB + buf * 256 + (32 * kb + 8 * a + 4 * hl) * 4);
; #pragma unroll
;                     for (int e = 0; e < 4; ++e) { const int r = 4 * a + e; if (kb) s1[r] = s1[r] * SC2 + c4[e]; else s0[r] = s0[r] * SC2 + c4[e]; }
;                 }
;             if (__builtin_amdgcn_readfirstlane((int)fmask)) {
; #pragma unroll
;                 for (int r = 0; r < 16; ++r) {
;                     const int key = kbase + 8 * (r >> 2) + (r & 3);
;                     if (key > t) s0[r] = -INFINITY;
;                     if (key + 32 > t) s1[r] = -INFINITY;
;                 }
;             }
.LBB0_194:
	v_add_u32_e32 v14, v134, v135
	v_add_u32_e32 v0, v136, v135
	v_add_u32_e32 v156, v138, v139
	ds_read_b128 v[170:173], v14 offset:9216
	ds_read_b128 v[174:177], v0 offset:9216
	ds_read_b128 v[178:181], v14 offset:9248
	ds_read_b128 v[182:185], v0 offset:9248
	ds_read_b128 v[186:189], v14 offset:9280
	ds_read_b128 v[194:197], v0 offset:9280
	ds_read_b128 v[198:201], v14 offset:9312
	ds_read_b128 v[202:205], v0 offset:9312
	ds_read_b128 v[144:147], v135 offset:43264
	ds_read_b128 v[148:151], v135 offset:43296
	ds_read_b128 v[152:155], v135 offset:43328
	ds_read_b128 v[12:15], v135 offset:43360
	s_or_b32 s1, s0, 63
	v_cmp_gt_i32_e32 vcc, s1, v125
	s_waitcnt lgkmcnt(11)
	v_mfma_f32_32x32x16_bf16 v[80:95], v[170:173], v[104:107], v[48:63]
	ds_read_b64_tr_b16 v[206:207], v156 offset:30720
	ds_read_b64_tr_b16 v[208:209], v156 offset:32256
	s_waitcnt lgkmcnt(12)
	v_mfma_f32_32x32x16_bf16 v[64:79], v[174:177], v[104:107], v[48:63]
	ds_read_b64_tr_b16 v[210:211], v156 offset:33792
	ds_read_b64_tr_b16 v[212:213], v156 offset:35328
	s_waitcnt lgkmcnt(13)
	v_mfma_f32_32x32x16_bf16 v[80:95], v[178:181], v[96:99], v[80:95]
	ds_read_b64_tr_b16 v[226:227], v156 offset:36864
	ds_read_b64_tr_b16 v[228:229], v156 offset:38400
	s_waitcnt lgkmcnt(14)
	v_mfma_f32_32x32x16_bf16 v[64:79], v[182:185], v[96:99], v[64:79]
	ds_read_b64_tr_b16 v[230:231], v156 offset:39936
	ds_read_b64_tr_b16 v[232:233], v156 offset:41472
	ds_read_b128 v[170:173], v135 offset:43392
	ds_read_b128 v[174:177], v135 offset:43424
	ds_read_b128 v[178:181], v135 offset:43456
	ds_read_b128 v[182:185], v135 offset:43488
	s_waitcnt lgkmcnt(15)
	v_mfma_f32_32x32x16_bf16 v[80:95], v[186:189], v[100:103], v[80:95]
	ds_read_b64_tr_b16 v[234:235], v156 offset:30784
	ds_read_b64_tr_b16 v[236:237], v156 offset:32320
	s_waitcnt lgkmcnt(15)
	v_mfma_f32_32x32x16_bf16 v[64:79], v[194:197], v[100:103], v[64:79]
	ds_read_b64_tr_b16 v[238:239], v156 offset:33856
	ds_read_b64_tr_b16 v[240:241], v156 offset:35392
	v_cndmask_b32_e64 v0, 0, 1, vcc
	s_nop 0
	v_readfirstlane_b32 s1, v0
	s_bitcmp0_b32 s1, 0
	s_waitcnt lgkmcnt(15)
	v_mfma_f32_32x32x16_bf16 v[80:95], v[198:201], v[108:111], v[80:95]
	ds_read_b64_tr_b16 v[242:243], v156 offset:36928
	ds_read_b64_tr_b16 v[244:245], v156 offset:38464
	s_waitcnt lgkmcnt(15)
	v_mfma_f32_32x32x16_bf16 v[64:79], v[202:205], v[108:111], v[64:79]
	ds_read_b64_tr_b16 v[246:247], v156 offset:40000
	ds_read_b64_tr_b16 v[248:249], v156 offset:41536
	s_waitcnt lgkmcnt(15)
	s_nop 5
	v_fma_f32 v82, v82, s54, v146
	v_fma_f32 v83, v83, s54, v147
	v_fma_f32 v86, v86, s54, v150
	v_fma_f32 v87, v87, s54, v151
	v_fma_f32 v88, v88, s54, v152
	v_fma_f32 v89, v89, s54, v153
	v_fma_f32 v10, v94, s54, v14
	v_fma_f32 v11, v95, s54, v15
	v_fma_f32 v12, v92, s54, v12
	v_fma_f32 v13, v93, s54, v13
	v_fma_f32 v14, v90, s54, v154
	v_fma_f32 v15, v91, s54, v155
	v_fma_f32 v84, v84, s54, v148
	v_fma_f32 v85, v85, s54, v149
	v_fma_f32 v80, v80, s54, v144
	v_fma_f32 v81, v81, s54, v145
	s_waitcnt lgkmcnt(8)
	v_fma_f32 v66, v66, s54, v172
	v_fma_f32 v67, v67, s54, v173
	v_fma_f32 v70, v70, s54, v176
	v_fma_f32 v71, v71, s54, v177
	v_fma_f32 v74, v74, s54, v180
	v_fma_f32 v75, v75, s54, v181
	v_fma_f32 v78, v78, s54, v184
	v_fma_f32 v79, v79, s54, v185
	v_fma_f32 v76, v76, s54, v182
	v_fma_f32 v77, v77, s54, v183
	v_fma_f32 v72, v72, s54, v178
	v_fma_f32 v73, v73, s54, v179
	v_fma_f32 v68, v68, s54, v174
	v_fma_f32 v69, v69, s54, v175
	v_fma_f32 v64, v64, s54, v170
	v_fma_f32 v65, v65, s54, v171
	s_cbranch_scc1 .LBB0_196
	v_or_b32_e32 v0, s0, v137
	v_or_b32_e32 v90, 32, v0
	v_cmp_le_i32_e32 vcc, v90, v126
	v_or_b32_e32 v90, 33, v0
	s_nop 0
	v_cndmask_b32_e32 v64, v220, v64, vcc
	v_cmp_lt_i32_e32 vcc, v0, v126
	s_nop 1
	v_cndmask_b32_e32 v81, v220, v81, vcc
	v_cmp_le_i32_e32 vcc, v0, v126
	s_nop 1
	v_cndmask_b32_e32 v80, v220, v80, vcc
	v_cmp_le_i32_e32 vcc, v90, v126
	v_or_b32_e32 v90, 2, v0
	s_nop 0
	v_cndmask_b32_e32 v65, v220, v65, vcc
	v_cmp_le_i32_e32 vcc, v90, v126
	v_or_b32_e32 v90, 34, v0
	s_nop 0
	v_cndmask_b32_e32 v82, v220, v82, vcc
	v_cmp_le_i32_e32 vcc, v90, v126
	v_or_b32_e32 v90, 3, v0
	s_nop 0
	v_cndmask_b32_e32 v66, v220, v66, vcc
	v_cmp_le_i32_e32 vcc, v90, v126
	v_or_b32_e32 v90, 35, v0
	s_nop 0
	v_cndmask_b32_e32 v83, v220, v83, vcc
	v_cmp_le_i32_e32 vcc, v90, v126
	v_or_b32_e32 v90, 8, v0
	s_nop 0
	v_cndmask_b32_e32 v67, v220, v67, vcc
	v_cmp_le_i32_e32 vcc, v90, v126
	v_or_b32_e32 v90, 40, v0
	s_nop 0
	v_cndmask_b32_e32 v84, v220, v84, vcc
	v_cmp_le_i32_e32 vcc, v90, v126
	v_or_b32_e32 v90, 9, v0
	s_nop 0
	v_cndmask_b32_e32 v68, v220, v68, vcc
	v_cmp_le_i32_e32 vcc, v90, v126
	v_or_b32_e32 v90, 41, v0
	s_nop 0
	v_cndmask_b32_e32 v85, v220, v85, vcc
	v_cmp_le_i32_e32 vcc, v90, v126
	v_or_b32_e32 v90, 10, v0
	s_nop 0
	v_cndmask_b32_e32 v69, v220, v69, vcc
	v_cmp_le_i32_e32 vcc, v90, v126
	v_or_b32_e32 v90, 42, v0
	s_nop 0
	v_cndmask_b32_e32 v86, v220, v86, vcc
	v_cmp_le_i32_e32 vcc, v90, v126
	v_or_b32_e32 v90, 11, v0
	s_nop 0
	v_cndmask_b32_e32 v70, v220, v70, vcc
	v_cmp_le_i32_e32 vcc, v90, v126
	v_or_b32_e32 v90, 43, v0
	s_nop 0
	v_cndmask_b32_e32 v87, v220, v87, vcc
	v_cmp_le_i32_e32 vcc, v90, v126
	v_or_b32_e32 v90, 16, v0
	s_nop 0
	v_cndmask_b32_e32 v71, v220, v71, vcc
	v_cmp_le_i32_e32 vcc, v90, v126
	v_or_b32_e32 v90, 48, v0
	s_nop 0
	v_cndmask_b32_e32 v88, v220, v88, vcc
	v_cmp_le_i32_e32 vcc, v90, v126
	v_or_b32_e32 v90, 17, v0
	s_nop 0
	v_cndmask_b32_e32 v72, v220, v72, vcc
	v_cmp_le_i32_e32 vcc, v90, v126
	v_or_b32_e32 v90, 49, v0
	s_nop 0
	v_cndmask_b32_e32 v89, v220, v89, vcc
	v_cmp_le_i32_e32 vcc, v90, v126
	v_or_b32_e32 v90, 18, v0
	s_nop 0
	v_cndmask_b32_e32 v73, v220, v73, vcc
	v_cmp_le_i32_e32 vcc, v90, v126
	v_or_b32_e32 v90, 50, v0
	s_nop 0
	v_cndmask_b32_e32 v14, v220, v14, vcc
	v_cmp_le_i32_e32 vcc, v90, v126
	v_or_b32_e32 v90, 19, v0
	s_nop 0
	v_cndmask_b32_e32 v74, v220, v74, vcc
	v_cmp_le_i32_e32 vcc, v90, v126
	v_or_b32_e32 v90, 51, v0
	s_nop 0
	v_cndmask_b32_e32 v15, v220, v15, vcc
	v_cmp_le_i32_e32 vcc, v90, v126
	v_or_b32_e32 v90, 24, v0
	s_nop 0
	v_cndmask_b32_e32 v75, v220, v75, vcc
	v_cmp_le_i32_e32 vcc, v90, v126
	v_or_b32_e32 v90, 56, v0
	s_nop 0
	v_cndmask_b32_e32 v12, v220, v12, vcc
	v_cmp_le_i32_e32 vcc, v90, v126
	v_or_b32_e32 v90, 25, v0
	s_nop 0
	v_cndmask_b32_e32 v76, v220, v76, vcc
	v_cmp_le_i32_e32 vcc, v90, v126
	v_or_b32_e32 v90, 57, v0
	s_nop 0
	v_cndmask_b32_e32 v13, v220, v13, vcc
	v_cmp_le_i32_e32 vcc, v90, v126
	v_or_b32_e32 v90, 26, v0
	s_nop 0
	v_cndmask_b32_e32 v77, v220, v77, vcc
	v_cmp_le_i32_e32 vcc, v90, v126
	v_or_b32_e32 v90, 58, v0
	s_nop 0
	v_cndmask_b32_e32 v10, v220, v10, vcc
	v_cmp_le_i32_e32 vcc, v90, v126
	v_or_b32_e32 v90, 27, v0
	v_or_b32_e32 v0, 59, v0
	v_cndmask_b32_e32 v78, v220, v78, vcc
	v_cmp_le_i32_e32 vcc, v90, v126
	s_nop 1
	v_cndmask_b32_e32 v11, v220, v11, vcc
	v_cmp_le_i32_e32 vcc, v0, v126
	s_nop 1
	v_cndmask_b32_e32 v79, v220, v79, vcc
